# v82 + invswap: grid-barrier XCD leader releases its local workgroups (XGEN add) before its own buffer_inv acquire instead of after it
# speedup vs baseline: 1.0040x; 1.0040x over previous
.LBB0_516:
	s_or_b64 exec, exec, s[8:9]
	s_mov_b64 s[8:9], exec
	v_mbcnt_lo_u32_b32 v1, s8, 0
	v_mbcnt_hi_u32_b32 v1, s9, v1
	v_cmp_eq_u32_e32 vcc, 0, v1
	s_and_saveexec_b64 s[12:13], vcc
	s_cbranch_execz .LBB0_518
	s_bcnt1_i32_b64 s8, s[8:9]
	v_mov_b32_e32 v1, 0x2000
	v_mov_b32_e32 v2, s8
	global_atomic_add v1, v2, s[6:7] offset:1024
.LBB0_518:
	s_or_b64 exec, exec, s[12:13]
	buffer_inv sc1
	s_waitcnt vmcnt(0)

.LBB0_779:
	s_or_b64 exec, exec, s[14:15]
	s_mov_b64 s[14:15], exec
	v_mbcnt_lo_u32_b32 v2, s14, 0
	v_mbcnt_hi_u32_b32 v2, s15, v2
	v_cmp_eq_u32_e32 vcc, 0, v2
	s_and_saveexec_b64 s[18:19], vcc
	s_cbranch_execz .LBB0_781
	s_bcnt1_i32_b64 s7, s[14:15]
	v_readlane_b32 s8, v255, 6
	v_mov_b32_e32 v2, s7
	v_readlane_b32 s9, v255, 7
	s_nop 4
	global_atomic_add v181, v2, s[8:9]
.LBB0_781:
	s_or_b64 exec, exec, s[18:19]
	buffer_inv sc1
	s_waitcnt vmcnt(0)

.LBB0_994:
	s_or_b64 exec, exec, s[14:15]
	s_mov_b64 s[14:15], exec
	v_mbcnt_lo_u32_b32 v2, s14, 0
	v_mbcnt_hi_u32_b32 v2, s15, v2
	v_cmp_eq_u32_e32 vcc, 0, v2
	s_and_saveexec_b64 s[18:19], vcc
	s_cbranch_execz .LBB0_996
	s_bcnt1_i32_b64 s6, s[14:15]
	v_mov_b32_e32 v2, s6
	v_readlane_b32 s6, v255, 6
	v_readlane_b32 s7, v255, 7
	s_nop 4
	global_atomic_add v181, v2, s[6:7]

.LBB0_1403:
	s_or_b64 exec, exec, s[18:19]
	s_mov_b64 s[18:19], exec
	v_mbcnt_lo_u32_b32 v2, s18, 0
	v_mbcnt_hi_u32_b32 v2, s19, v2
	v_cmp_eq_u32_e32 vcc, 0, v2
	s_and_saveexec_b64 s[22:23], vcc
	s_cbranch_execz .LBB0_1405
	s_bcnt1_i32_b64 s7, s[18:19]
	v_readlane_b32 s8, v255, 6
	v_mov_b32_e32 v2, s7
	v_readlane_b32 s9, v255, 7
	s_nop 4
	global_atomic_add v181, v2, s[8:9]
.LBB0_1405:
	s_or_b64 exec, exec, s[22:23]
	buffer_inv sc1
	s_waitcnt vmcnt(0)

.LBB0_1548:
	s_or_b64 exec, exec, s[10:11]
	s_mov_b64 s[10:11], exec
	v_mbcnt_lo_u32_b32 v2, s10, 0
	v_mbcnt_hi_u32_b32 v2, s11, v2
	v_cmp_eq_u32_e32 vcc, 0, v2
	s_and_saveexec_b64 s[14:15], vcc
	s_cbranch_execz .LBB0_1550
	s_bcnt1_i32_b64 s6, s[10:11]
	v_mov_b32_e32 v2, s6
	v_readlane_b32 s6, v255, 6
	v_readlane_b32 s7, v255, 7
	s_nop 4
	global_atomic_add v181, v2, s[6:7]
.LBB0_1550:
	s_or_b64 exec, exec, s[14:15]
	buffer_inv sc1
	s_waitcnt vmcnt(0)

.LBB0_2443:
	s_or_b64 exec, exec, s[2:3]
	s_mov_b64 s[2:3], exec
	v_mbcnt_lo_u32_b32 v0, s2, 0
	v_mbcnt_hi_u32_b32 v0, s3, v0
	v_cmp_eq_u32_e32 vcc, 0, v0
	s_and_saveexec_b64 s[4:5], vcc
	s_cbranch_execz .LBB0_2445
	s_bcnt1_i32_b64 s2, s[2:3]
	v_mov_b32_e32 v1, s2
	v_readlane_b32 s2, v255, 6
	v_mov_b32_e32 v0, 0
	v_readlane_b32 s3, v255, 7
	s_nop 4
	global_atomic_add v0, v1, s[2:3]
.LBB0_2445:
	s_or_b64 exec, exec, s[4:5]
	buffer_inv sc1
	s_waitcnt vmcnt(0)
